# attnA: waves 4-7 staggered half a step (barrier mid-step), V DMA lags K by one tile
# baseline (speedup 1.0000x reference)
; __device__ __forceinline__ void attnA_unit(const P2Ctx& C, int b, int h, int qb) {
;     ...
;     const int kkey = 8 * wid + (lane >> 3), kchs = (lane & 7) ^ ((kkey >> 1) & 7);
;     const bf16_t* ksrc = C.Kb + ((size_t)trow0 + kkey) * DM + h * 128 + kchs * 8;
;     const bf16_t* vsrc[2];
; #pragma unroll
;     for (int i = 0; i < 2; ++i) { const int p = 2 * wid + i, kg = p >> 1, cbv = 2 * (p & 1) + (lane >> 5), vkey = kg * 8 + ((lane >> 2) & 7), vch = cbv * 4 + (lane & 3);
;         vsrc[i] = C.Vb + ((size_t)trow0 + vkey) * DM + h * 128 + vch * 8; }
;     ...
;     A_DMA(0); A_DMA(1);
.LBB0_572:
	s_andn2_b64 vcc, exec, s[6:7]
	s_cbranch_vccnz .LBB0_614
	s_sub_i32 s6, s37, 32
	s_and_b32 s11, s6, 7
	s_lshr_b32 s6, s6, 3
	s_sub_i32 s10, 15, s6
	s_lshr_b32 s8, s83, 2
	s_and_b32 s9, s83, 3
	s_lshl_b32 s12, s10, 1
	s_add_i32 s12, s12, 2
	s_lshr_b32 s6, s9, 1
	s_lshl_b32 s13, s10, 1
	s_add_i32 s13, s13, s6
	s_add_i32 s13, s13, 1
	s_lshl_b32 s22, s83, 10
	s_lshl_b32 s23, s83, 11
	s_add_i32 s23, s23, 0x4000
	s_lshl_b32 s6, s10, 7
	s_lshl_b32 s7, s9, 5
	s_add_i32 s15, s6, s7
	s_add_i32 s26, s15, 0xffffff01
	s_mov_b32 s25, 0
	v_and_b32_e32 v100, 31, v219
	v_lshrrev_b32_e32 v101, 5, v219
	s_load_dwordx2 s[20:21], s[62:63], 0x80
	v_lshlrev_b32_e32 v107, 4, v196
	s_waitcnt lgkmcnt(0)
	v_cmp_gt_u32_e32 vcc, 32, v196
	s_and_saveexec_b64 s[6:7], vcc
	global_load_dwordx4 v[108:111], v107, s[20:21]
	s_or_b64 exec, exec, s[6:7]
	s_lshl_b32 s6, s11, 11
	s_add_i32 s6, s6, s15
	s_lshl_b32 s6, s6, 11
	s_lshl_b32 s7, s81, 1
	s_add_i32 s6, s6, s7
	s_lshl_b32 s7, s8, 7
	s_add_i32 s6, s6, s7
	s_add_u32 s20, s76, s6
	s_addc_u32 s21, s77, 0
	v_lshlrev_b32_e32 v102, 11, v100
	v_lshl_add_u32 v102, v101, 4, v102
	global_load_dwordx4 v[164:167], v102, s[20:21]
	global_load_dwordx4 v[168:171], v102, s[20:21] offset:32
	global_load_dwordx4 v[172:175], v102, s[20:21] offset:64
	global_load_dwordx4 v[176:179], v102, s[20:21] offset:96
	s_lshl_b32 s6, s11, 22
	s_lshl_b32 s7, s81, 1
	s_add_i32 s6, s6, s7
	s_add_u32 s16, s72, s6
	s_addc_u32 s17, s73, 0
	s_add_u32 s18, s74, s6
	s_addc_u32 s19, s75, 0
	s_mov_b32 s24, 0
	v_lshrrev_b32_e32 v103, 3, v219
	s_lshl_b32 s6, s83, 3
	v_add_u32_e32 v103, s6, v103
	v_bfe_u32 v104, v103, 1, 3
	v_and_b32_e32 v105, 7, v219
	v_xor_b32_e32 v104, v104, v105
	v_lshlrev_b32_e32 v104, 4, v104
	v_lshl_add_u32 v197, v103, 11, v104
	v_bfe_u32 v103, v219, 2, 3
	v_add_u32_e32 v103, s6, v103
	v_and_b32_e32 v104, 3, v219
	v_lshlrev_b32_e32 v104, 4, v104
	v_lshl_add_u32 v104, v101, 6, v104
	v_lshl_add_u32 v198, v103, 11, v104
	s_and_b32 s6, s24, 3
	s_lshl_b32 s6, s6, 15
	s_add_i32 s7, s6, s22
	s_mov_b32 m0, s7
	s_add_u32 s20, s16, 0x80
	s_addc_u32 s21, s17, 0
	s_nop 0
	global_load_lds_dwordx4 v197, s[16:17]
	s_add_i32 m0, s7, 0x2000
	s_add_u32 s16, s16, 0x20000
	s_addc_u32 s17, s17, 0
	s_nop 0
	global_load_lds_dwordx4 v197, s[20:21]
	s_add_i32 s24, s24, 1
	s_and_b32 s6, s24, 3
	s_lshl_b32 s6, s6, 15
	s_add_i32 s7, s6, s22
	s_mov_b32 m0, s7
	s_add_u32 s20, s16, 0x80
	s_addc_u32 s21, s17, 0
	s_nop 0
	global_load_lds_dwordx4 v197, s[16:17]
	s_add_i32 m0, s7, 0x2000
	s_add_u32 s16, s16, 0x20000
	s_addc_u32 s17, s17, 0
	s_nop 0
	global_load_lds_dwordx4 v197, s[20:21]
	s_add_i32 s6, s24, -1
	s_and_b32 s6, s6, 3
	s_lshl_b32 s6, s6, 15
	s_add_i32 s29, s6, s23
	s_mov_b32 m0, s29
	s_add_u32 s20, s18, 0x80
	s_addc_u32 s21, s19, 0
	s_nop 0
	global_load_lds_dwordx4 v198, s[18:19]
	s_add_i32 m0, s29, 0x400
	s_add_u32 s18, s18, 0x20000
	s_addc_u32 s19, s19, 0
	s_nop 0
	global_load_lds_dwordx4 v198, s[20:21]
	s_add_i32 s24, s24, 1
	v_bfe_u32 v103, v100, 1, 3
	v_lshlrev_b32_e32 v104, 7, v100
	s_lshl_b32 s6, s8, 13
	v_add_u32_e32 v104, s6, v104
	v_or_b32_e32 v105, 0, v101
	v_xor_b32_e32 v105, v105, v103
	v_lshl_add_u32 v200, v105, 4, v104
	v_or_b32_e32 v105, 2, v101
	v_xor_b32_e32 v105, v105, v103
	v_lshl_add_u32 v201, v105, 4, v104
	v_or_b32_e32 v105, 4, v101
	v_xor_b32_e32 v105, v105, v103
	v_lshl_add_u32 v202, v105, 4, v104
	v_or_b32_e32 v105, 6, v101
	v_xor_b32_e32 v105, v105, v103
	v_lshl_add_u32 v203, v105, 4, v104
	v_bfe_u32 v103, v219, 2, 2
	v_lshl_add_u32 v103, v101, 2, v103
	v_lshlrev_b32_e32 v103, 6, v103
	v_bfe_u32 v104, v219, 4, 1
	v_lshl_add_u32 v103, v104, 5, v103
	v_and_b32_e32 v104, 3, v219
	v_lshl_add_u32 v103, v104, 3, v103
	v_add_u32_e32 v204, 0x4000, v103
	s_sub_i32 s6, 0x120, s15
	s_lshl_b32 s6, s6, 2
	s_add_i32 s6, s6, 0x22400
	v_lshlrev_b32_e32 v103, 4, v101
	v_lshlrev_b32_e32 v104, 2, v100
	v_sub_u32_e32 v103, v103, v104
	v_add_u32_e32 v236, s6, v103
	v_cmp_gt_u32_e32 vcc, 0x160, v196
	s_and_saveexec_b64 s[6:7], vcc
	s_cbranch_execz .LaA_padskip_1
	v_subrev_u32_e32 v103, 0x60, v196
	v_max_i32_e32 v104, 0, v103
	v_lshl_add_u32 v104, v104, 2, s42
	ds_read_b32 v105, v104
	v_cmp_gt_i32_e32 vcc, 0, v103
	v_mov_b32_e32 v106, 0x22400
	v_lshl_add_u32 v104, v196, 2, v106
	s_waitcnt lgkmcnt(0)
	v_cndmask_b32_e64 v105, v105, 0, vcc
	ds_write_b32 v104, v105
; #define A_WAITBAR(ahead) do { if ((ahead) >= 2) asm volatile("s_waitcnt vmcnt(8)" ::: "memory"); else if ((ahead) == 1) asm volatile("s_waitcnt vmcnt(4)" ::: "memory"); else asm volatile("s_waitcnt vmcnt(0)" ::: "memory"); \
;         __builtin_amdgcn_s_barrier(); asm volatile("" ::: "memory"); } while (0)
; __device__ __forceinline__ void attnA_unit(const P2Ctx& C, int b, int h, int qb) {
;     ...
;     f32x16 o[4];
; #pragma unroll
;     for (int cb = 0; cb < 4; ++cb)
; #pragma unroll
;         for (int r = 0; r < 16; ++r) o[cb][r] = 0.f;
;     float mhat = 0.f, l = 0.f;
;     bf16x8 pf_[4];
; #pragma unroll
;     for (int i = 0; i < 4; ++i) pf_[i] = (bf16x8){0, 0, 0, 0, 0, 0, 0, 0};
;     ...
;     A_DMA(0); A_DMA(1);
;     A_WAITBAR(1);
;     { if (2 < NT && !(pf & 16)) A_DMA(2);
.LaA_padskip_1:
	s_or_b64 exec, exec, s[6:7]
	v_mov_b32_e32 v4, 0
	v_mov_b32_e32 v5, 0
	v_mov_b32_e32 v6, 0
	v_mov_b32_e32 v7, 0
	v_mov_b32_e32 v8, 0
	v_mov_b32_e32 v9, 0
	v_mov_b32_e32 v10, 0
	v_mov_b32_e32 v11, 0
	v_mov_b32_e32 v12, 0
	v_mov_b32_e32 v13, 0
	v_mov_b32_e32 v14, 0
	v_mov_b32_e32 v15, 0
	v_mov_b32_e32 v16, 0
	v_mov_b32_e32 v17, 0
	v_mov_b32_e32 v18, 0
	v_mov_b32_e32 v19, 0
	v_mov_b32_e32 v20, 0
	v_mov_b32_e32 v21, 0
	v_mov_b32_e32 v22, 0
	v_mov_b32_e32 v23, 0
	v_mov_b32_e32 v24, 0
	v_mov_b32_e32 v25, 0
	v_mov_b32_e32 v26, 0
	v_mov_b32_e32 v27, 0
	v_mov_b32_e32 v28, 0
	v_mov_b32_e32 v29, 0
	v_mov_b32_e32 v30, 0
	v_mov_b32_e32 v31, 0
	v_mov_b32_e32 v32, 0
	v_mov_b32_e32 v33, 0
	v_mov_b32_e32 v34, 0
	v_mov_b32_e32 v35, 0
	v_mov_b32_e32 v36, 0
	v_mov_b32_e32 v37, 0
	v_mov_b32_e32 v38, 0
	v_mov_b32_e32 v39, 0
	v_mov_b32_e32 v40, 0
	v_mov_b32_e32 v41, 0
	v_mov_b32_e32 v42, 0
	v_mov_b32_e32 v43, 0
	v_mov_b32_e32 v44, 0
	v_mov_b32_e32 v45, 0
	v_mov_b32_e32 v46, 0
	v_mov_b32_e32 v47, 0
	v_mov_b32_e32 v48, 0
	v_mov_b32_e32 v49, 0
	v_mov_b32_e32 v50, 0
	v_mov_b32_e32 v51, 0
	v_mov_b32_e32 v52, 0
	v_mov_b32_e32 v53, 0
	v_mov_b32_e32 v54, 0
	v_mov_b32_e32 v55, 0
	v_mov_b32_e32 v56, 0
	v_mov_b32_e32 v57, 0
	v_mov_b32_e32 v58, 0
	v_mov_b32_e32 v59, 0
	v_mov_b32_e32 v60, 0
	v_mov_b32_e32 v61, 0
	v_mov_b32_e32 v62, 0
	v_mov_b32_e32 v63, 0
	v_mov_b32_e32 v64, 0
	v_mov_b32_e32 v65, 0
	v_mov_b32_e32 v66, 0
	v_mov_b32_e32 v67, 0
	v_mov_b32_e32 v220, 0
	v_mov_b32_e32 v221, 0
	v_mov_b32_e32 v222, 0
	v_mov_b32_e32 v223, 0
	v_mov_b32_e32 v224, 0
	v_mov_b32_e32 v225, 0
	v_mov_b32_e32 v226, 0
	v_mov_b32_e32 v227, 0
	v_mov_b32_e32 v228, 0
	v_mov_b32_e32 v229, 0
	v_mov_b32_e32 v230, 0
	v_mov_b32_e32 v231, 0
	v_mov_b32_e32 v232, 0
	v_mov_b32_e32 v233, 0
	v_mov_b32_e32 v234, 0
	v_mov_b32_e32 v235, 0
	v_mov_b32_e32 v240, 0
	v_mov_b32_e32 v241, 0
	s_mov_b32 s14, 0
	s_waitcnt vmcnt(4) lgkmcnt(0)
	v_cmp_gt_u32_e32 vcc, 32, v196
	v_add_u32_e32 v107, 0x22a00, v107
	s_and_saveexec_b64 s[6:7], vcc
	ds_write_b128 v107, v[108:111]
	s_or_b64 exec, exec, s[6:7]
	s_waitcnt lgkmcnt(0)
	s_barrier
	s_cmp_le_u32 s24, s12
	s_cbranch_scc0 .LaA_nodma_2
	s_cmp_lt_u32 s24, s12
	s_cbranch_scc0 .LaA_nok_3
	s_and_b32 s6, s24, 3
	s_lshl_b32 s6, s6, 15
	s_add_i32 s7, s6, s22
	s_mov_b32 m0, s7
	s_add_u32 s20, s16, 0x80
	s_addc_u32 s21, s17, 0
	s_nop 0
	global_load_lds_dwordx4 v197, s[16:17]
	s_add_i32 m0, s7, 0x2000
	s_add_u32 s16, s16, 0x20000
	s_addc_u32 s17, s17, 0
	s_nop 0
	global_load_lds_dwordx4 v197, s[20:21]
.LaA_nok_3:
	s_add_i32 s6, s24, -1
	s_and_b32 s6, s6, 3
	s_lshl_b32 s6, s6, 15
	s_add_i32 s29, s6, s23
	s_mov_b32 m0, s29
	s_add_u32 s20, s18, 0x80
	s_addc_u32 s21, s19, 0
	s_nop 0
	global_load_lds_dwordx4 v198, s[18:19]
	s_add_i32 m0, s29, 0x400
	s_add_u32 s18, s18, 0x20000
	s_addc_u32 s19, s19, 0
	s_nop 0
	global_load_lds_dwordx4 v198, s[20:21]
	s_add_i32 s24, s24, 1

; #define A_MAX() \
;         float mx = fmaxf(s[0][0], s[1][0]); \
;         _Pragma("unroll") for (int r = 1; r < 16; ++r) mx = fmaxf(fmaxf(mx, s[0][r]), s[1][r]); \
;         mx = fmaxf(mx, __shfl_xor(mx, 32));
; __device__ __forceinline__ void attnA_unit(const P2Ctx& C, int b, int h, int qb) {
;     ...
;       A_QK(0)
;       if (!(pf & 4)) {
;       A_MAX()
;       mhat = mx;
; #pragma unroll
;       for (int kb2 = 0; kb2 < 2; ++kb2)
; #pragma unroll
;           for (int r = 0; r < 16; ++r) s[kb2][r] -= mx;
.LaA_far0_5:
	v_max_f32_e32 v242, v68, v69
	v_max_f32_e32 v243, v84, v85
	v_max3_f32 v242, v242, v70, v71
	v_max3_f32 v243, v243, v86, v87
	v_max3_f32 v242, v242, v72, v73
	v_max3_f32 v243, v243, v88, v89
	v_max3_f32 v242, v242, v74, v75
	v_max3_f32 v243, v243, v90, v91
	v_max3_f32 v242, v242, v76, v77
	v_max3_f32 v243, v243, v92, v93
	v_max3_f32 v242, v242, v78, v79
	v_max3_f32 v243, v243, v94, v95
	v_max3_f32 v242, v242, v80, v81
	v_max3_f32 v243, v243, v96, v97
	v_max3_f32 v242, v242, v82, v83
	v_max3_f32 v243, v243, v98, v99
	v_max_f32_e32 v242, v242, v243
	v_mov_b32_e32 v243, v242
	s_nop 1
	v_permlane32_swap_b32 v243, v242
	v_max_f32_e32 v247, v243, v242
	v_mov_b32_e32 v240, v247
	v_sub_f32_e32 v68, v68, v247
	v_sub_f32_e32 v69, v69, v247
	v_sub_f32_e32 v70, v70, v247
	v_sub_f32_e32 v71, v71, v247
	v_sub_f32_e32 v72, v72, v247
	v_sub_f32_e32 v73, v73, v247
	v_sub_f32_e32 v74, v74, v247
	v_sub_f32_e32 v75, v75, v247
	v_sub_f32_e32 v76, v76, v247
	v_sub_f32_e32 v77, v77, v247
	v_sub_f32_e32 v78, v78, v247
	v_sub_f32_e32 v79, v79, v247
	v_sub_f32_e32 v80, v80, v247
	v_sub_f32_e32 v81, v81, v247
	v_sub_f32_e32 v82, v82, v247
	v_sub_f32_e32 v83, v83, v247
	v_sub_f32_e32 v84, v84, v247
	v_sub_f32_e32 v85, v85, v247
	v_sub_f32_e32 v86, v86, v247
	v_sub_f32_e32 v87, v87, v247
	v_sub_f32_e32 v88, v88, v247
	v_sub_f32_e32 v89, v89, v247
	v_sub_f32_e32 v90, v90, v247
	v_sub_f32_e32 v91, v91, v247
	v_sub_f32_e32 v92, v92, v247
	v_sub_f32_e32 v93, v93, v247
	v_sub_f32_e32 v94, v94, v247
	v_sub_f32_e32 v95, v95, v247
	v_sub_f32_e32 v96, v96, v247
	v_sub_f32_e32 v97, v97, v247
	v_sub_f32_e32 v98, v98, v247
	v_sub_f32_e32 v99, v99, v247
	v_xor_b32_e32 v220, 0x80000000, v247
	v_xor_b32_e32 v221, 0x80000000, v247
	v_xor_b32_e32 v222, 0x80000000, v247
	v_xor_b32_e32 v223, 0x80000000, v247
	v_xor_b32_e32 v224, 0x80000000, v247
	v_xor_b32_e32 v225, 0x80000000, v247
	v_xor_b32_e32 v226, 0x80000000, v247
	v_xor_b32_e32 v227, 0x80000000, v247
	v_xor_b32_e32 v228, 0x80000000, v247
	v_xor_b32_e32 v229, 0x80000000, v247
	v_xor_b32_e32 v230, 0x80000000, v247
	v_xor_b32_e32 v231, 0x80000000, v247
	v_xor_b32_e32 v232, 0x80000000, v247
	v_xor_b32_e32 v233, 0x80000000, v247
	v_xor_b32_e32 v234, 0x80000000, v247
	v_xor_b32_e32 v235, 0x80000000, v247
	s_cmp_eq_u32 s8, 1
	s_cbranch_scc0 .LaA_g_6
	s_add_i32 s6, s14, 2
	s_cmp_lt_u32 s6, s12
	s_cbranch_scc1 .LaA_w4_7
	s_waitcnt vmcnt(0)
	s_branch .LaA_wd_8

; #define A_WAITBAR(ahead) do { if ((ahead) >= 2) asm volatile("s_waitcnt vmcnt(8)" ::: "memory"); else if ((ahead) == 1) asm volatile("s_waitcnt vmcnt(4)" ::: "memory"); else asm volatile("s_waitcnt vmcnt(0)" ::: "memory"); \
;         __builtin_amdgcn_s_barrier(); asm volatile("" ::: "memory"); } while (0)
; __device__ __forceinline__ void attnA_unit(const P2Ctx& C, int b, int h, int qb) {
;     ...
;       { const int lastt = NT - 1 < 2 ? NT - 1 : 2; A_WAITBAR(lastt - 1); } }
;     for (int kt = 1; kt < NT; ++kt) {
;         if (kt + 2 < NT && !(pf & 16)) A_DMA(kt + 2);
.LaA_wd_8:
	s_barrier
	s_cmp_le_u32 s24, s12
	s_cbranch_scc0 .LaA_nodma_9
	s_cmp_lt_u32 s24, s12
	s_cbranch_scc0 .LaA_nok_10
	s_and_b32 s6, s24, 3
	s_lshl_b32 s6, s6, 15
	s_add_i32 s7, s6, s22
	s_mov_b32 m0, s7
	s_add_u32 s20, s16, 0x80
	s_addc_u32 s21, s17, 0
	s_nop 0
	global_load_lds_dwordx4 v197, s[16:17]
	s_add_i32 m0, s7, 0x2000
	s_add_u32 s16, s16, 0x20000
	s_addc_u32 s17, s17, 0
	s_nop 0
	global_load_lds_dwordx4 v197, s[20:21]

; #define A_WAITBAR(ahead) do { if ((ahead) >= 2) asm volatile("s_waitcnt vmcnt(8)" ::: "memory"); else if ((ahead) == 1) asm volatile("s_waitcnt vmcnt(4)" ::: "memory"); else asm volatile("s_waitcnt vmcnt(0)" ::: "memory"); \
;         __builtin_amdgcn_s_barrier(); asm volatile("" ::: "memory"); } while (0)
; #define EX4_(S, B) do { S[B] = fexp2(S[B]); S[B + 1] = fexp2(S[B + 1]); S[B + 2] = fexp2(S[B + 2]); S[B + 3] = fexp2(S[B + 3]); } while (0)
; #define SUM8_(S, B) do { ps += ((S[B] + S[B + 1]) + (S[B + 2] + S[B + 3])) + ((S[B + 4] + S[B + 5]) + (S[B + 6] + S[B + 7])); } while (0)
; __device__ __forceinline__ void attnA_unit(const P2Ctx& C, int b, int h, int qb) {
;     ...
;       float ps = 0.f;
;       EX4_(s[0], 0); EX4_(s[0], 4); EX4_(s[0], 8); EX4_(s[0], 12); EX4_(s[1], 0); EX4_(s[1], 4); EX4_(s[1], 8); EX4_(s[1], 12);
;       SUM8_(s[0], 0); SUM8_(s[0], 8); SUM8_(s[1], 0); SUM8_(s[1], 8);
;       l = ps;
;       pf_[0] = pack_p(s[0], 0); pf_[1] = pack_p(s[0], 1); pf_[2] = pack_p(s[1], 0); pf_[3] = pack_p(s[1], 1); }
;       { const int lastt = NT - 1 < 2 ? NT - 1 : 2; A_WAITBAR(lastt - 1); } }
.LaA_nodma_9:
.LaA_g_6:
	v_exp_f32_e32 v68, v68
	v_exp_f32_e32 v69, v69
	v_exp_f32_e32 v70, v70
	v_exp_f32_e32 v71, v71
	v_exp_f32_e32 v72, v72
	v_exp_f32_e32 v73, v73
	v_exp_f32_e32 v74, v74
	v_exp_f32_e32 v75, v75
	v_exp_f32_e32 v76, v76
	v_exp_f32_e32 v77, v77
	v_exp_f32_e32 v78, v78
	v_exp_f32_e32 v79, v79
	v_exp_f32_e32 v80, v80
	v_exp_f32_e32 v81, v81
	v_exp_f32_e32 v82, v82
	v_exp_f32_e32 v83, v83
	v_exp_f32_e32 v84, v84
	v_exp_f32_e32 v85, v85
	v_exp_f32_e32 v86, v86
	v_exp_f32_e32 v87, v87
	v_exp_f32_e32 v88, v88
	v_exp_f32_e32 v89, v89
	v_exp_f32_e32 v90, v90
	v_exp_f32_e32 v91, v91
	v_exp_f32_e32 v92, v92
	v_exp_f32_e32 v93, v93
	v_exp_f32_e32 v94, v94
	v_exp_f32_e32 v95, v95
	v_exp_f32_e32 v96, v96
	v_exp_f32_e32 v97, v97
	v_exp_f32_e32 v98, v98
	v_exp_f32_e32 v99, v99
	v_add_f32_e32 v245, v68, v69
	v_add_f32_e32 v243, v70, v71
	v_add_f32_e32 v245, v245, v243
	v_add_f32_e32 v243, v72, v73
	v_add_f32_e32 v242, v74, v75
	v_add_f32_e32 v243, v243, v242
	v_add_f32_e32 v245, v245, v243
	v_add_f32_e32 v246, v76, v77
	v_add_f32_e32 v243, v78, v79
	v_add_f32_e32 v246, v246, v243
	v_add_f32_e32 v243, v80, v81
	v_add_f32_e32 v242, v82, v83
	v_add_f32_e32 v243, v243, v242
	v_add_f32_e32 v246, v246, v243
	v_add_f32_e32 v245, v245, v246
	v_add_f32_e32 v246, v84, v85
	v_add_f32_e32 v243, v86, v87
	v_add_f32_e32 v246, v246, v243
	v_add_f32_e32 v243, v88, v89
	v_add_f32_e32 v242, v90, v91
	v_add_f32_e32 v243, v243, v242
	v_add_f32_e32 v246, v246, v243
	v_add_f32_e32 v245, v245, v246
	v_add_f32_e32 v246, v92, v93
	v_add_f32_e32 v243, v94, v95
	v_add_f32_e32 v246, v246, v243
	v_add_f32_e32 v243, v96, v97
	v_add_f32_e32 v242, v98, v99
	v_add_f32_e32 v243, v243, v242
	v_add_f32_e32 v246, v246, v243
	v_add_f32_e32 v245, v245, v246
	v_mov_b32_e32 v241, v245
	v_cvt_pk_bf16_f32 v180, v68, v69
	v_cvt_pk_bf16_f32 v181, v70, v71
	v_cvt_pk_bf16_f32 v182, v72, v73
	v_cvt_pk_bf16_f32 v183, v74, v75
	v_cvt_pk_bf16_f32 v184, v76, v77
	v_cvt_pk_bf16_f32 v185, v78, v79
	v_cvt_pk_bf16_f32 v186, v80, v81
	v_cvt_pk_bf16_f32 v187, v82, v83
	v_cvt_pk_bf16_f32 v188, v84, v85
	v_cvt_pk_bf16_f32 v189, v86, v87
	v_cvt_pk_bf16_f32 v190, v88, v89
	v_cvt_pk_bf16_f32 v191, v90, v91
	v_cvt_pk_bf16_f32 v192, v92, v93
	v_cvt_pk_bf16_f32 v193, v94, v95
	v_cvt_pk_bf16_f32 v194, v96, v97
	v_cvt_pk_bf16_f32 v195, v98, v99
	s_cmp_eq_u32 s8, 0
	s_cbranch_scc0 .LaA_g_11
	s_add_i32 s6, s14, 2
	s_cmp_lt_u32 s6, s12
	s_cbranch_scc1 .LaA_w4_12
	s_waitcnt vmcnt(0)
	s_branch .LaA_wd_13

; __device__ __forceinline__ void attnA_unit(const P2Ctx& C, int b, int h, int qb) {
;     ...
;     for (int kt = 1; kt < NT; ++kt) {
;         if (kt + 2 < NT && !(pf & 16)) A_DMA(kt + 2);
.LaA_g_11:
	s_mov_b32 s14, 1
.LaA_loop:
	s_cmp_eq_u32 s8, 0
	s_cbranch_scc0 .LaA_g_14
	s_cmp_le_u32 s24, s12
	s_cbranch_scc0 .LaA_nodma_15
	s_cmp_lt_u32 s24, s12
	s_cbranch_scc0 .LaA_nok_16
	s_and_b32 s6, s24, 3
	s_lshl_b32 s6, s6, 15
	s_add_i32 s7, s6, s22
	s_mov_b32 m0, s7
	s_add_u32 s20, s16, 0x80
	s_addc_u32 s21, s17, 0
	s_nop 0
	global_load_lds_dwordx4 v197, s[16:17]
	s_add_i32 m0, s7, 0x2000
	s_add_u32 s16, s16, 0x20000
	s_addc_u32 s17, s17, 0
	s_nop 0
	global_load_lds_dwordx4 v197, s[20:21]

; #define LAS __attribute__((address_space(3)))
; __device__ __forceinline__ float fexp2(float x) { return __builtin_amdgcn_exp2f(x); }
; #define MFMA32(a, b, c) __builtin_amdgcn_mfma_f32_32x32x16_bf16((a), (b), (c), 0, 0, 0)
; __device__ __forceinline__ bf16x8 v_build(const VRaw& r, int ks) { return (bf16x8){r.lo[ks][0], r.lo[ks][1], r.lo[ks][2], r.lo[ks][3], r.hv[ks][0], r.hv[ks][1], r.hv[ks][2], r.hv[ks][3]}; }
; #define SB_ __builtin_amdgcn_sched_barrier(0)
; #define A_MAX() \
;         float mx = fmaxf(s[0][0], s[1][0]); \
;         _Pragma("unroll") for (int r = 1; r < 16; ++r) mx = fmaxf(fmaxf(mx, s[0][r]), s[1][r]); \
;         mx = fmaxf(mx, __shfl_xor(mx, 32));
; #define EX4_(S, B) do { S[B] = fexp2(S[B]); S[B + 1] = fexp2(S[B + 1]); S[B + 2] = fexp2(S[B + 2]); S[B + 3] = fexp2(S[B + 3]); } while (0)
; __device__ __forceinline__ void attnA_unit(const P2Ctx& C, int b, int h, int qb) {
;     ...
;         if (kt < ntw) {
;             A_QK(kt)
;             if (!(pf & 4)) {
;             const LAS unsigned char* vimg = lds + ((kt - 1) & 3) * 32768 + 16384;
;             VRaw va;
;             v_issue<4>(vimg, 0, lane, va);
;             A_MAX()
;             float fres = 1.0f; bool resc = false;
;             if (__any(mx > ATHR)) {
;                 const float dl = fmaxf(mx, 0.f);
;                 mhat += dl;
;                 fres = fexp2(-dl); resc = true;
; #pragma unroll
;                 for (int kb2 = 0; kb2 < 2; ++kb2)
; #pragma unroll
;                     for (int r = 0; r < 16; ++r) s[kb2][r] -= dl;
;             }
;             float ps = 0.f;
;             v_wait(va);
;             __builtin_amdgcn_s_setprio(1);
; #pragma unroll
;             for (int ks = 0; ks < 4; ++ks) o[0] = MFMA32(v_build(va, ks), pf_[ks], o[0]);
;             EX4_(s[0], 0); EX4_(s[0], 4); EX4_(s[0], 8); EX4_(s[0], 12);
;             SB_; v_issue<4>(vimg, 1, lane, va); v_wait(va);
.LaA_nodma_15:
.LaA_g_14:
	s_cmp_lt_u32 s14, s13
	s_cbranch_scc0 .LaA_pvonly
	s_and_b32 s6, s14, 3
	s_lshl_b32 s6, s6, 15
	s_add_i32 s7, s14, -1
	s_and_b32 s7, s7, 3
	s_lshl_b32 s7, s7, 15
	v_add_u32_e32 v248, s6, v200
	v_add_u32_e32 v249, s6, v201
	v_add_u32_e32 v250, s6, v202
	v_add_u32_e32 v251, s6, v203
	v_add_u32_e32 v237, s7, v204
	ds_read_b128 v[100:103], v248
	ds_read_b128 v[104:107], v248 offset:4096
	ds_read_b128 v[108:111], v249
	ds_read_b128 v[112:115], v249 offset:4096
	ds_read_b128 v[116:119], v250
	ds_read_b128 v[120:123], v250 offset:4096
	ds_read_b128 v[124:127], v251
	ds_read_b128 v[128:131], v251 offset:4096
	s_waitcnt lgkmcnt(7)
	v_mfma_f32_32x32x16_bf16 v[68:83], v[100:103], v[164:167], v[220:235]
	ds_read_b64_tr_b16 v[132:133], v237 offset:0
	ds_read_b64_tr_b16 v[134:135], v237 offset:2048
	s_waitcnt lgkmcnt(8)
	v_mfma_f32_32x32x16_bf16 v[84:99], v[104:107], v[164:167], v[220:235]
	ds_read_b64_tr_b16 v[136:137], v237 offset:4096
	ds_read_b64_tr_b16 v[138:139], v237 offset:6144
	s_waitcnt lgkmcnt(9)
	v_mfma_f32_32x32x16_bf16 v[68:83], v[108:111], v[168:171], v[68:83]
	ds_read_b64_tr_b16 v[140:141], v237 offset:8192
	ds_read_b64_tr_b16 v[142:143], v237 offset:10240
	s_waitcnt lgkmcnt(10)
	v_mfma_f32_32x32x16_bf16 v[84:99], v[112:115], v[168:171], v[84:99]
	ds_read_b64_tr_b16 v[144:145], v237 offset:12288
	ds_read_b64_tr_b16 v[146:147], v237 offset:14336
	s_waitcnt lgkmcnt(11)
	v_mfma_f32_32x32x16_bf16 v[68:83], v[116:119], v[172:175], v[68:83]
	s_waitcnt lgkmcnt(10)
	v_mfma_f32_32x32x16_bf16 v[84:99], v[120:123], v[172:175], v[84:99]
	s_waitcnt lgkmcnt(9)
	v_mfma_f32_32x32x16_bf16 v[68:83], v[124:127], v[176:179], v[68:83]
	s_waitcnt lgkmcnt(8)
	v_mfma_f32_32x32x16_bf16 v[84:99], v[128:131], v[176:179], v[84:99]
	s_waitcnt lgkmcnt(0)
	v_mfma_f32_32x32x16_bf16 v[4:19], v[132:135], v[180:183], v[4:19]
	ds_read_b64_tr_b16 v[148:149], v237 offset:512
	ds_read_b64_tr_b16 v[150:151], v237 offset:2560
	v_mfma_f32_32x32x16_bf16 v[4:19], v[136:139], v[184:187], v[4:19]
	ds_read_b64_tr_b16 v[152:153], v237 offset:4608
	ds_read_b64_tr_b16 v[154:155], v237 offset:6656
	v_mfma_f32_32x32x16_bf16 v[4:19], v[140:143], v[188:191], v[4:19]
	ds_read_b64_tr_b16 v[156:157], v237 offset:8704
	ds_read_b64_tr_b16 v[158:159], v237 offset:10752
	v_mfma_f32_32x32x16_bf16 v[4:19], v[144:147], v[192:195], v[4:19]
	ds_read_b64_tr_b16 v[160:161], v237 offset:12800
	ds_read_b64_tr_b16 v[162:163], v237 offset:14848
	s_lshl_b32 s6, s14, 6
	s_cmp_gt_i32 s6, s26
	s_cbranch_scc1 .LaA_near_17

; #define A_WAITBAR(ahead) do { if ((ahead) >= 2) asm volatile("s_waitcnt vmcnt(8)" ::: "memory"); else if ((ahead) == 1) asm volatile("s_waitcnt vmcnt(4)" ::: "memory"); else asm volatile("s_waitcnt vmcnt(0)" ::: "memory"); \
;         __builtin_amdgcn_s_barrier(); asm volatile("" ::: "memory"); } while (0)
; __device__ __forceinline__ void attnA_unit(const P2Ctx& C, int b, int h, int qb) {
;     ...
;         { const int lastt = NT - 1 < kt + 2 ? NT - 1 : kt + 2; const int ahead = lastt - (kt + 1); A_WAITBAR(ahead); }
.LaA_resc_back:
	s_cmp_eq_u32 s8, 1
	s_cbranch_scc0 .LaA_g_19
	s_add_i32 s6, s14, 2
	s_cmp_lt_u32 s6, s12
	s_cbranch_scc1 .LaA_w4_20
	s_waitcnt vmcnt(0)
	s_branch .LaA_wd_21

; #define MFMA32(a, b, c) __builtin_amdgcn_mfma_f32_32x32x16_bf16((a), (b), (c), 0, 0, 0)
; __device__ __forceinline__ bf16x8 v_build(const VRaw& r, int ks) { return (bf16x8){r.lo[ks][0], r.lo[ks][1], r.lo[ks][2], r.lo[ks][3], r.hv[ks][0], r.hv[ks][1], r.hv[ks][2], r.hv[ks][3]}; }
; #define SB_ __builtin_amdgcn_sched_barrier(0)
; #define EX4_(S, B) do { S[B] = fexp2(S[B]); S[B + 1] = fexp2(S[B + 1]); S[B + 2] = fexp2(S[B + 2]); S[B + 3] = fexp2(S[B + 3]); } while (0)
; #define SUM8_(S, B) do { ps += ((S[B] + S[B + 1]) + (S[B + 2] + S[B + 3])) + ((S[B + 4] + S[B + 5]) + (S[B + 6] + S[B + 7])); } while (0)
; __device__ __forceinline__ void attnA_unit(const P2Ctx& C, int b, int h, int qb) {
;     ...
;             SB_; v_issue<4>(vimg, 1, lane, va); v_wait(va);
; #pragma unroll
;             for (int ks = 0; ks < 4; ++ks) o[1] = MFMA32(v_build(va, ks), pf_[ks], o[1]);
;             EX4_(s[1], 0); EX4_(s[1], 4); EX4_(s[1], 8); EX4_(s[1], 12);
;             SB_; v_issue<4>(vimg, 2, lane, va); v_wait(va);
; #pragma unroll
;             for (int ks = 0; ks < 4; ++ks) o[2] = MFMA32(v_build(va, ks), pf_[ks], o[2]);
;             SUM8_(s[0], 0); SUM8_(s[0], 8); SUM8_(s[1], 0); SUM8_(s[1], 8);
;             SB_; v_issue<4>(vimg, 3, lane, va); v_wait(va);
;             o[3] = MFMA32(v_build(va, 0), pf_[0], o[3]); pf_[0] = pack_p(s[0], 0);
;             o[3] = MFMA32(v_build(va, 1), pf_[1], o[3]); pf_[1] = pack_p(s[0], 1);
;             o[3] = MFMA32(v_build(va, 2), pf_[2], o[3]); pf_[2] = pack_p(s[1], 0);
;             o[3] = MFMA32(v_build(va, 3), pf_[3], o[3]); pf_[3] = pack_p(s[1], 1);
.LaA_nodma_22:
.LaA_g_19:
	s_waitcnt lgkmcnt(0)
	v_mfma_f32_32x32x16_bf16 v[36:51], v[132:135], v[180:183], v[36:51]
	ds_read_b64_tr_b16 v[148:149], v237 offset:1536
	ds_read_b64_tr_b16 v[150:151], v237 offset:3584
	v_exp_f32_e32 v68, v68
	v_exp_f32_e32 v69, v69
	v_exp_f32_e32 v70, v70
	v_exp_f32_e32 v71, v71
	v_mfma_f32_32x32x16_bf16 v[36:51], v[136:139], v[184:187], v[36:51]
	ds_read_b64_tr_b16 v[152:153], v237 offset:5632
	ds_read_b64_tr_b16 v[154:155], v237 offset:7680
	v_exp_f32_e32 v72, v72
	v_exp_f32_e32 v73, v73
	v_exp_f32_e32 v74, v74
	v_exp_f32_e32 v75, v75
	v_mfma_f32_32x32x16_bf16 v[36:51], v[140:143], v[188:191], v[36:51]
	ds_read_b64_tr_b16 v[156:157], v237 offset:9728
	ds_read_b64_tr_b16 v[158:159], v237 offset:11776
	v_exp_f32_e32 v76, v76
	v_exp_f32_e32 v77, v77
	v_exp_f32_e32 v78, v78
	v_exp_f32_e32 v79, v79
	v_mfma_f32_32x32x16_bf16 v[36:51], v[144:147], v[192:195], v[36:51]
	ds_read_b64_tr_b16 v[160:161], v237 offset:13824
	ds_read_b64_tr_b16 v[162:163], v237 offset:15872
	v_exp_f32_e32 v80, v80
	v_exp_f32_e32 v81, v81
	v_exp_f32_e32 v82, v82
	v_exp_f32_e32 v83, v83
	s_waitcnt lgkmcnt(0)
	v_mfma_f32_32x32x16_bf16 v[52:67], v[148:151], v[180:183], v[52:67]
	v_exp_f32_e32 v84, v84
	v_exp_f32_e32 v85, v85
	v_exp_f32_e32 v86, v86
	v_exp_f32_e32 v87, v87
	v_exp_f32_e32 v88, v88
	v_exp_f32_e32 v89, v89
	v_exp_f32_e32 v90, v90
	v_exp_f32_e32 v91, v91
	v_cvt_pk_bf16_f32 v180, v68, v69
	v_cvt_pk_bf16_f32 v181, v70, v71
	v_cvt_pk_bf16_f32 v182, v72, v73
	v_cvt_pk_bf16_f32 v183, v74, v75
	v_mfma_f32_32x32x16_bf16 v[52:67], v[152:155], v[184:187], v[52:67]
	v_exp_f32_e32 v92, v92
	v_exp_f32_e32 v93, v93
	v_exp_f32_e32 v94, v94
	v_exp_f32_e32 v95, v95
	v_exp_f32_e32 v96, v96
	v_exp_f32_e32 v97, v97
	v_exp_f32_e32 v98, v98
	v_exp_f32_e32 v99, v99
	v_cvt_pk_bf16_f32 v184, v76, v77
	v_cvt_pk_bf16_f32 v185, v78, v79
	v_cvt_pk_bf16_f32 v186, v80, v81
	v_cvt_pk_bf16_f32 v187, v82, v83
	v_mfma_f32_32x32x16_bf16 v[52:67], v[156:159], v[188:191], v[52:67]
	v_add_f32_e32 v245, v68, v69
	v_add_f32_e32 v243, v70, v71
	v_add_f32_e32 v245, v245, v243
	v_add_f32_e32 v243, v72, v73
	v_add_f32_e32 v242, v74, v75
	v_add_f32_e32 v243, v243, v242
	v_add_f32_e32 v245, v245, v243
	v_add_f32_e32 v246, v76, v77
	v_add_f32_e32 v243, v78, v79
	v_add_f32_e32 v246, v246, v243
	v_add_f32_e32 v243, v80, v81
	v_add_f32_e32 v242, v82, v83
	v_add_f32_e32 v243, v243, v242
	v_add_f32_e32 v246, v246, v243
	v_add_f32_e32 v245, v245, v246
	v_cvt_pk_bf16_f32 v188, v84, v85
	v_cvt_pk_bf16_f32 v189, v86, v87
	v_cvt_pk_bf16_f32 v190, v88, v89
	v_cvt_pk_bf16_f32 v191, v90, v91
	v_mfma_f32_32x32x16_bf16 v[52:67], v[160:163], v[192:195], v[52:67]
	v_add_f32_e32 v246, v84, v85
	v_add_f32_e32 v243, v86, v87
	v_add_f32_e32 v246, v246, v243
	v_add_f32_e32 v243, v88, v89
	v_add_f32_e32 v242, v90, v91
	v_add_f32_e32 v243, v243, v242
	v_add_f32_e32 v246, v246, v243
	v_add_f32_e32 v245, v245, v246
	v_add_f32_e32 v246, v92, v93
	v_add_f32_e32 v243, v94, v95
	v_add_f32_e32 v246, v246, v243
	v_add_f32_e32 v243, v96, v97
	v_add_f32_e32 v242, v98, v99
	v_add_f32_e32 v243, v243, v242
	v_add_f32_e32 v246, v246, v243
	v_add_f32_e32 v245, v245, v246
	v_cvt_pk_bf16_f32 v192, v92, v93
	v_cvt_pk_bf16_f32 v193, v94, v95
	v_cvt_pk_bf16_f32 v194, v96, v97
	v_cvt_pk_bf16_f32 v195, v98, v99
	s_cmp_lg_u32 s25, 0
	s_cbranch_scc1 .LaA_resc_post

; #define A_WAITBAR(ahead) do { if ((ahead) >= 2) asm volatile("s_waitcnt vmcnt(8)" ::: "memory"); else if ((ahead) == 1) asm volatile("s_waitcnt vmcnt(4)" ::: "memory"); else asm volatile("s_waitcnt vmcnt(0)" ::: "memory"); \
;         __builtin_amdgcn_s_barrier(); asm volatile("" ::: "memory"); } while (0)
; __device__ __forceinline__ void attnA_unit(const P2Ctx& C, int b, int h, int qb) {
;     ...
;         { const int lastt = NT - 1 < kt + 2 ? NT - 1 : kt + 2; const int ahead = lastt - (kt + 1); A_WAITBAR(ahead); }
.LaA_stepend:
	s_cmp_eq_u32 s8, 0
	s_cbranch_scc0 .LaA_g_24
	s_add_i32 s6, s14, 2
	s_cmp_lt_u32 s6, s12
	s_cbranch_scc1 .LaA_w4_25
	s_waitcnt vmcnt(0)
	s_branch .LaA_wd_26

; #define A_WAITBAR(ahead) do { if ((ahead) >= 2) asm volatile("s_waitcnt vmcnt(8)" ::: "memory"); else if ((ahead) == 1) asm volatile("s_waitcnt vmcnt(4)" ::: "memory"); else asm volatile("s_waitcnt vmcnt(0)" ::: "memory"); \
;         __builtin_amdgcn_s_barrier(); asm volatile("" ::: "memory"); } while (0)
; __device__ __forceinline__ void attnA_unit(const P2Ctx& C, int b, int h, int qb) {
;     ...
;         { const int lastt = NT - 1 < kt + 2 ? NT - 1 : kt + 2; const int ahead = lastt - (kt + 1); A_WAITBAR(ahead); }
;     }
.LaA_g_24:
	s_add_i32 s14, s14, 1
	s_cmp_lt_u32 s14, s12
	s_cbranch_scc1 .LaA_loop
	s_branch .LaA_loopexit

; __device__ __forceinline__ void attnA_unit(const P2Ctx& C, int b, int h, int qb) {
;     ...
;         } else if (kt - 1 < ntw && !(pf & 2)) { A_PV(kt - 1); }
.LaA_nodma_31:
.LaA_g_28:
	s_cmp_eq_u32 s14, s13
	s_cbranch_scc0 .LaA_pvskip_27
	s_add_i32 s7, s14, -1
	s_and_b32 s7, s7, 3
	s_lshl_b32 s7, s7, 15
	v_add_u32_e32 v237, s7, v204
	ds_read_b64_tr_b16 v[132:133], v237 offset:0
	ds_read_b64_tr_b16 v[134:135], v237 offset:2048
	ds_read_b64_tr_b16 v[136:137], v237 offset:4096
	ds_read_b64_tr_b16 v[138:139], v237 offset:6144
	ds_read_b64_tr_b16 v[140:141], v237 offset:8192
	ds_read_b64_tr_b16 v[142:143], v237 offset:10240
	ds_read_b64_tr_b16 v[144:145], v237 offset:12288
	ds_read_b64_tr_b16 v[146:147], v237 offset:14336
	s_waitcnt lgkmcnt(0)
	v_mfma_f32_32x32x16_bf16 v[4:19], v[132:135], v[180:183], v[4:19]
	ds_read_b64_tr_b16 v[148:149], v237 offset:512
	ds_read_b64_tr_b16 v[150:151], v237 offset:2560
	v_mfma_f32_32x32x16_bf16 v[4:19], v[136:139], v[184:187], v[4:19]
	ds_read_b64_tr_b16 v[152:153], v237 offset:4608
	ds_read_b64_tr_b16 v[154:155], v237 offset:6656
	v_mfma_f32_32x32x16_bf16 v[4:19], v[140:143], v[188:191], v[4:19]
	ds_read_b64_tr_b16 v[156:157], v237 offset:8704
	ds_read_b64_tr_b16 v[158:159], v237 offset:10752
	v_mfma_f32_32x32x16_bf16 v[4:19], v[144:147], v[192:195], v[4:19]
	ds_read_b64_tr_b16 v[160:161], v237 offset:12800
	ds_read_b64_tr_b16 v[162:163], v237 offset:14848
	s_waitcnt lgkmcnt(0)
	v_mfma_f32_32x32x16_bf16 v[20:35], v[148:151], v[180:183], v[20:35]
	ds_read_b64_tr_b16 v[132:133], v237 offset:1024
	ds_read_b64_tr_b16 v[134:135], v237 offset:3072
	v_mfma_f32_32x32x16_bf16 v[20:35], v[152:155], v[184:187], v[20:35]
	ds_read_b64_tr_b16 v[136:137], v237 offset:5120
	ds_read_b64_tr_b16 v[138:139], v237 offset:7168
	v_mfma_f32_32x32x16_bf16 v[20:35], v[156:159], v[188:191], v[20:35]
	ds_read_b64_tr_b16 v[140:141], v237 offset:9216
	ds_read_b64_tr_b16 v[142:143], v237 offset:11264
	v_mfma_f32_32x32x16_bf16 v[20:35], v[160:163], v[192:195], v[20:35]
	ds_read_b64_tr_b16 v[144:145], v237 offset:13312
	ds_read_b64_tr_b16 v[146:147], v237 offset:15360
	s_waitcnt lgkmcnt(0)
	v_mfma_f32_32x32x16_bf16 v[36:51], v[132:135], v[180:183], v[36:51]
	ds_read_b64_tr_b16 v[148:149], v237 offset:1536
	ds_read_b64_tr_b16 v[150:151], v237 offset:3584
	v_mfma_f32_32x32x16_bf16 v[36:51], v[136:139], v[184:187], v[36:51]
	ds_read_b64_tr_b16 v[152:153], v237 offset:5632
	ds_read_b64_tr_b16 v[154:155], v237 offset:7680
	v_mfma_f32_32x32x16_bf16 v[36:51], v[140:143], v[188:191], v[36:51]
	ds_read_b64_tr_b16 v[156:157], v237 offset:9728
	ds_read_b64_tr_b16 v[158:159], v237 offset:11776
	v_mfma_f32_32x32x16_bf16 v[36:51], v[144:147], v[192:195], v[36:51]
	ds_read_b64_tr_b16 v[160:161], v237 offset:13824
	ds_read_b64_tr_b16 v[162:163], v237 offset:15872
	s_waitcnt lgkmcnt(0)
	v_mfma_f32_32x32x16_bf16 v[52:67], v[148:151], v[180:183], v[52:67]
	v_mfma_f32_32x32x16_bf16 v[52:67], v[152:155], v[184:187], v[52:67]
	v_mfma_f32_32x32x16_bf16 v[52:67], v[156:159], v[188:191], v[52:67]
	v_mfma_f32_32x32x16_bf16 v[52:67], v[160:163], v[192:195], v[52:67]

; #define LAS __attribute__((address_space(3)))
; __device__ __forceinline__ void attnA_unit(const P2Ctx& C, int b, int h, int qb) {
;     ...
;     __syncthreads();
;     ...
;     l += __shfl_xor(l, 32);
;     const float inv = 1.0f / l;
;     LAS float* X2 = (LAS float*)(lds + 65536);
;     if (comp == 1) {
; #pragma unroll
;         for (int cb = 0; cb < 4; ++cb)
; #pragma unroll
;             for (int r = 0; r < 16; ++r) X2[((qs * 4 + cb) * 16 + r) * 64 + lane] = o[cb][r] * inv;
;     }
.LaA_nofinalpv_33:
	s_waitcnt lgkmcnt(0)
	s_barrier
	v_mov_b32_e32 v243, v241
	s_nop 1
	v_permlane32_swap_b32 v243, v241
	v_add_f32_e32 v241, v243, v241
	v_rcp_f32_e32 v241, v241
	s_lshl_b32 s6, s9, 14
	s_add_i32 s6, s6, 0x10000
	v_lshlrev_b32_e32 v2, 2, v219
	v_add_u32_e32 v2, s6, v2
	s_cmp_eq_u32 s8, 0
	s_cbranch_scc1 .LaA_comp0_34
	s_nop 7
	s_nop 3
	v_mul_f32_e32 v68, v4, v241
	ds_write_b32 v2, v68 offset:0
	v_mul_f32_e32 v69, v5, v241
	ds_write_b32 v2, v69 offset:256
	v_mul_f32_e32 v68, v6, v241
	ds_write_b32 v2, v68 offset:512
	v_mul_f32_e32 v69, v7, v241
	ds_write_b32 v2, v69 offset:768
	v_mul_f32_e32 v68, v8, v241
	ds_write_b32 v2, v68 offset:1024
	v_mul_f32_e32 v69, v9, v241
	ds_write_b32 v2, v69 offset:1280
	v_mul_f32_e32 v68, v10, v241
	ds_write_b32 v2, v68 offset:1536
	v_mul_f32_e32 v69, v11, v241
	ds_write_b32 v2, v69 offset:1792
	v_mul_f32_e32 v68, v12, v241
	ds_write_b32 v2, v68 offset:2048
	v_mul_f32_e32 v69, v13, v241
	ds_write_b32 v2, v69 offset:2304
	v_mul_f32_e32 v68, v14, v241
	ds_write_b32 v2, v68 offset:2560
	v_mul_f32_e32 v69, v15, v241
	ds_write_b32 v2, v69 offset:2816
	v_mul_f32_e32 v68, v16, v241
	ds_write_b32 v2, v68 offset:3072
	v_mul_f32_e32 v69, v17, v241
	ds_write_b32 v2, v69 offset:3328
	v_mul_f32_e32 v68, v18, v241
	ds_write_b32 v2, v68 offset:3584
	v_mul_f32_e32 v69, v19, v241
	ds_write_b32 v2, v69 offset:3840
	v_mul_f32_e32 v68, v20, v241
	ds_write_b32 v2, v68 offset:4096
	v_mul_f32_e32 v69, v21, v241
	ds_write_b32 v2, v69 offset:4352
	v_mul_f32_e32 v68, v22, v241
	ds_write_b32 v2, v68 offset:4608
	v_mul_f32_e32 v69, v23, v241
	ds_write_b32 v2, v69 offset:4864
	v_mul_f32_e32 v68, v24, v241
	ds_write_b32 v2, v68 offset:5120
	v_mul_f32_e32 v69, v25, v241
	ds_write_b32 v2, v69 offset:5376
	v_mul_f32_e32 v68, v26, v241
	ds_write_b32 v2, v68 offset:5632
	v_mul_f32_e32 v69, v27, v241
	ds_write_b32 v2, v69 offset:5888
	v_mul_f32_e32 v68, v28, v241
	ds_write_b32 v2, v68 offset:6144
	v_mul_f32_e32 v69, v29, v241
	ds_write_b32 v2, v69 offset:6400
	v_mul_f32_e32 v68, v30, v241
	ds_write_b32 v2, v68 offset:6656
	v_mul_f32_e32 v69, v31, v241
	ds_write_b32 v2, v69 offset:6912
	v_mul_f32_e32 v68, v32, v241
	ds_write_b32 v2, v68 offset:7168
	v_mul_f32_e32 v69, v33, v241
	ds_write_b32 v2, v69 offset:7424
	v_mul_f32_e32 v68, v34, v241
	ds_write_b32 v2, v68 offset:7680
	v_mul_f32_e32 v69, v35, v241
	ds_write_b32 v2, v69 offset:7936
	v_mul_f32_e32 v68, v36, v241
	ds_write_b32 v2, v68 offset:8192
	v_mul_f32_e32 v69, v37, v241
	ds_write_b32 v2, v69 offset:8448
	v_mul_f32_e32 v68, v38, v241
	ds_write_b32 v2, v68 offset:8704
	v_mul_f32_e32 v69, v39, v241
	ds_write_b32 v2, v69 offset:8960
	v_mul_f32_e32 v68, v40, v241
	ds_write_b32 v2, v68 offset:9216
	v_mul_f32_e32 v69, v41, v241
	ds_write_b32 v2, v69 offset:9472
	v_mul_f32_e32 v68, v42, v241
	ds_write_b32 v2, v68 offset:9728
	v_mul_f32_e32 v69, v43, v241
	ds_write_b32 v2, v69 offset:9984
	v_mul_f32_e32 v68, v44, v241
	ds_write_b32 v2, v68 offset:10240
	v_mul_f32_e32 v69, v45, v241
	ds_write_b32 v2, v69 offset:10496
	v_mul_f32_e32 v68, v46, v241
	ds_write_b32 v2, v68 offset:10752
	v_mul_f32_e32 v69, v47, v241
	ds_write_b32 v2, v69 offset:11008
	v_mul_f32_e32 v68, v48, v241
	ds_write_b32 v2, v68 offset:11264
	v_mul_f32_e32 v69, v49, v241
	ds_write_b32 v2, v69 offset:11520
	v_mul_f32_e32 v68, v50, v241
	ds_write_b32 v2, v68 offset:11776
	v_mul_f32_e32 v69, v51, v241
	ds_write_b32 v2, v69 offset:12032
	v_mul_f32_e32 v68, v52, v241
	ds_write_b32 v2, v68 offset:12288
	v_mul_f32_e32 v69, v53, v241
	ds_write_b32 v2, v69 offset:12544
	v_mul_f32_e32 v68, v54, v241
	ds_write_b32 v2, v68 offset:12800
	v_mul_f32_e32 v69, v55, v241
	ds_write_b32 v2, v69 offset:13056
	v_mul_f32_e32 v68, v56, v241
	ds_write_b32 v2, v68 offset:13312
	v_mul_f32_e32 v69, v57, v241
	ds_write_b32 v2, v69 offset:13568
	v_mul_f32_e32 v68, v58, v241
	ds_write_b32 v2, v68 offset:13824
	v_mul_f32_e32 v69, v59, v241
	ds_write_b32 v2, v69 offset:14080
	v_mul_f32_e32 v68, v60, v241
	ds_write_b32 v2, v68 offset:14336
	v_mul_f32_e32 v69, v61, v241
	ds_write_b32 v2, v69 offset:14592
	v_mul_f32_e32 v68, v62, v241
	ds_write_b32 v2, v68 offset:14848
	v_mul_f32_e32 v69, v63, v241
	ds_write_b32 v2, v69 offset:15104
	v_mul_f32_e32 v68, v64, v241
	ds_write_b32 v2, v68 offset:15360
	v_mul_f32_e32 v69, v65, v241
	ds_write_b32 v2, v69 offset:15616
	v_mul_f32_e32 v68, v66, v241
	ds_write_b32 v2, v68 offset:15872
	v_mul_f32_e32 v69, v67, v241
	ds_write_b32 v2, v69 offset:16128
	s_waitcnt lgkmcnt(0)
	s_barrier
	s_branch .LaA_epiend_35
; __device__ __forceinline__ void attnA_unit(const P2Ctx& C, int b, int h, int qb) {
;     ...
;     if (comp == 1) {
; #pragma unroll
;         for (int cb = 0; cb < 4; ++cb)
; #pragma unroll
;             for (int r = 0; r < 16; ++r) X2[((qs * 4 + cb) * 16 + r) * 64 + lane] = o[cb][r] * inv;
;     }
	s_nop 0
	s_nop 0
	s_nop 0
	s_nop 0
	s_nop 0
	s_nop 0
	s_nop 0
	s_nop 0
	s_nop 0
	s_nop 0
	s_nop 0
	s_nop 0
	s_nop 0
	s_nop 0
	s_nop 0
	s_nop 0
	s_nop 0
	s_nop 0
	s_nop 0
	s_nop 0
	s_nop 0
	s_nop 0
	s_nop 0
	s_nop 0
	s_nop 0
	s_nop 0
	s_nop 0
	s_nop 0
	s_nop 0
	s_nop 0
	s_nop 0
	s_nop 0
	s_nop 0
	s_nop 0
	s_nop 0
	s_nop 0
	s_nop 0
	s_nop 0
	s_nop 0
	s_nop 0
	s_nop 0
	s_nop 0
	s_nop 0
	s_nop 0
	s_nop 0
	s_nop 0
	s_nop 0
	s_nop 0
	s_nop 0
	s_nop 0
	s_nop 0
	s_nop 0
	s_nop 0
	s_nop 0
	s_nop 0
	s_nop 0
	s_nop 0
	s_nop 0
	s_nop 0
	s_nop 0
	s_nop 0
	s_nop 0
	s_nop 0
	s_nop 0
	s_nop 0
	s_nop 0
	s_nop 0
	s_nop 0
	s_nop 0
	s_nop 0
	s_nop 0
	s_nop 0
	s_nop 0
	s_nop 0
	s_nop 0
	s_nop 0
	s_nop 0
	s_nop 0
	s_nop 0
	s_nop 0
	s_nop 0
	s_nop 0
	s_nop 0
	s_nop 0
	s_nop 0
	s_nop 0
	s_nop 0
	s_nop 0
	s_nop 0
	s_nop 0
	s_nop 0
	s_nop 0
	s_nop 0
	s_nop 0
	s_nop 0
	s_nop 0
	s_nop 0
	s_nop 0
	s_nop 0
	s_nop 0
	s_nop 0
	s_nop 0
	s_nop 0
	s_nop 0
	s_nop 0
	s_nop 0
	s_nop 0
	s_nop 0
	s_nop 0
	s_nop 0
	s_nop 0
	s_nop 0
	s_nop 0
	s_nop 0
	s_nop 0
	s_nop 0
	s_nop 0
	s_nop 0
	s_nop 0
	s_nop 0
	s_nop 0
	s_nop 0
	s_nop 0
	s_nop 0
	s_nop 0
	s_nop 0
	s_nop 0
	s_nop 0
	s_nop 0
	s_nop 0
	s_nop 0
	s_nop 0
	s_nop 0
	s_nop 0
	s_nop 0
	s_nop 0
	s_nop 0
	s_nop 0
	s_nop 0
	s_nop 0
	s_nop 0
	s_nop 0
	s_nop 0
	s_nop 0
	s_nop 0
	s_nop 0
	s_nop 0
	s_nop 0
	s_nop 0
	s_nop 0
	s_nop 0
	s_nop 0
	s_nop 0
	s_nop 0
	s_nop 0
	s_nop 0
	s_nop 0
	s_nop 0
	s_nop 0
	s_nop 0
	s_nop 0
	s_nop 0
	s_nop 0
	s_nop 0
	s_nop 0
	s_nop 0
	s_nop 0
	s_nop 0
	s_nop 0
	s_nop 0
	s_nop 0
	s_nop 0
	s_nop 0
	s_nop 0
	s_nop 0
	s_nop 0
	s_nop 0
	s_nop 0
	s_nop 0
	s_nop 0
	s_nop 0
	s_nop 0
	s_nop 0
	s_nop 0
	s_nop 0
	s_nop 0
	s_nop 0
	s_nop 0
	s_nop 0
	s_nop 0
	s_nop 0
	s_nop 0
	s_nop 0
	s_nop 0
	s_nop 0
	s_nop 0
	s_nop 0
	s_nop 0
	s_nop 0
	s_nop 0
	s_nop 0
	s_nop 0
	s_nop 0
	s_nop 0
	s_nop 0
	s_nop 0
	s_nop 0
	s_nop 0
	s_nop 0
	s_nop 0
	s_nop 0
	s_nop 0
	s_nop 0
	s_nop 0
	s_nop 0
	s_nop 0
	s_nop 0
	s_nop 0
	s_nop 0
	s_nop 0
	s_nop 0
	s_nop 0
	s_nop 0
	s_nop 0
	s_nop 0
	s_nop 0
	s_nop 0
	s_nop 0
	s_nop 0
	s_nop 0
	s_nop 0
	s_nop 0
	s_nop 0
	s_nop 0
	s_nop 0
	s_nop 0
	s_nop 0
	s_nop 0
	s_nop 0
	s_nop 0
	s_nop 0
	s_nop 0
	s_nop 0
	s_nop 0
	s_nop 0
	s_nop 0
	s_nop 0
	s_nop 0
	s_nop 0
	s_nop 0
	s_nop 0
	s_nop 0
	s_nop 0
	s_nop 0
	s_nop 0
	s_nop 0
	s_nop 0
	s_nop 0
	s_nop 0
	s_nop 0
	s_nop 0
	s_nop 0
	s_nop 0
	s_nop 0
	s_nop 0
	s_nop 0
	s_nop 0
	s_nop 0
	s_nop 0
	s_nop 0
	s_nop 0
	s_nop 0
	s_nop 0
	s_nop 0
	s_nop 0
	s_nop 0
	s_nop 0
	s_nop 0
	s_nop 0
	s_nop 0
	s_nop 0
	s_nop 0
	s_nop 0
	s_nop 0
	s_nop 0
	s_nop 0
	s_nop 0
	s_nop 0
	s_nop 0
	s_nop 0
	s_nop 0
	s_nop 0
	s_nop 0
	s_nop 0
	s_nop 0
	s_nop 0
	s_nop 0
	s_nop 0
	s_nop 0
	s_nop 0
	s_nop 0
	s_nop 0
	s_nop 0
	s_nop 0
	s_nop 0
	s_nop 0
	s_nop 0
	s_nop 0
	s_nop 0
	s_nop 0
	s_nop 0
	s_nop 0
	s_nop 0
	s_nop 0
	s_nop 0
	s_nop 0
	s_nop 0
	s_nop 0
	s_nop 0
	s_nop 0
	s_nop 0
	s_nop 0
	s_nop 0
	s_nop 0
	s_nop 0
	s_nop 0
	s_nop 0
	s_nop 0
	s_nop 0
	s_nop 0
	s_nop 0
	s_nop 0
	s_nop 0
	s_nop 0
	s_nop 0
	s_nop 0
	s_nop 0
	s_nop 0
	s_nop 0
	s_nop 0
	s_nop 0
	s_nop 0
	s_nop 0
	s_nop 0
	s_nop 0
	s_nop 0
	s_nop 0
	s_nop 0
	s_nop 0
	s_nop 0
	s_nop 0
	s_nop 0
	s_nop 0
	s_nop 0
	s_nop 0
	s_nop 0
	s_nop 0
	s_nop 0
	s_nop 0
	s_nop 0
	s_nop 0
	s_nop 0
	s_nop 0
	s_nop 0
	s_nop 0
	s_nop 0
	s_nop 0
	s_nop 0
	s_nop 0
	s_nop 0
	s_nop 0
	s_nop 0
	s_nop 0
	s_nop 0
	s_nop 0
	s_nop 0
	s_nop 0
	s_nop 0
	s_nop 0
	s_nop 0
	s_nop 0
	s_nop 0
	s_nop 0
	s_nop 0
	s_nop 0
	s_nop 0
	s_nop 0
	s_nop 0
	s_nop 0
	s_nop 0
	s_nop 0
	s_nop 0
	s_nop 0
	s_nop 0
	s_nop 0
	s_nop 0
	s_nop 0
	s_nop 0
	s_nop 0
	s_nop 0
	s_nop 0
	s_nop 0
	s_nop 0
	s_nop 0
	s_nop 0
	s_nop 0
	s_nop 0
	s_nop 0
	s_nop 0
	s_nop 0
	s_nop 0
	s_nop 0
	s_nop 0
	s_nop 0
	s_nop 0
	s_nop 0
	s_nop 0
	s_nop 0
	s_nop 0
	s_nop 0
	s_nop 0
	s_nop 0
	s_nop 0
	s_nop 0
	s_nop 0
	s_nop 0
	s_nop 0
	s_nop 0
	s_nop 0
	s_nop 0
	s_nop 0
	s_nop 0
	s_nop 0
	s_nop 0
	s_nop 0
	s_nop 0
	s_nop 0
	s_nop 0
	s_nop 0
	s_nop 0
	s_nop 0
	s_nop 0
	s_nop 0
	s_nop 0
	s_nop 0
	s_nop 0
	s_nop 0
	s_nop 0
	s_nop 0
	s_nop 0
	s_nop 0
	s_nop 0
	s_nop 0
	s_nop 0
	s_nop 0
	s_nop 0
	s_nop 0
	s_nop 0
	s_nop 0
	s_nop 0
	s_nop 0
	s_nop 0
	s_nop 0
	s_nop 0
	s_nop 0
	s_nop 0
	s_nop 0
	s_nop 0
	s_nop 0
	s_nop 0
	s_nop 0
	s_nop 0
	s_nop 0
	s_nop 0
	s_nop 0
	s_nop 0
	s_nop 0
	s_nop 0
	s_nop 0
	s_nop 0
	s_nop 0
	s_nop 0
	s_nop 0
	s_nop 0
	s_nop 0
	s_nop 0
	s_nop 0
	s_nop 0
	s_nop 0
	s_nop 0
	s_nop 0
	s_nop 0
	s_nop 0
	s_nop 0
	s_nop 0
	s_nop 0
	s_nop 0
	s_nop 0
	s_nop 0
	s_nop 0
	s_nop 0
	s_nop 0
	s_nop 0
	s_nop 0
	s_nop 0
	s_nop 0
	s_nop 0
	s_nop 0
	s_nop 0
	s_nop 0
	s_nop 0
	s_nop 0
	s_nop 0
	s_nop 0
	s_nop 0
	s_nop 0
	s_nop 0
	s_nop 0
	s_nop 0
	s_nop 0
	s_nop 0
	s_nop 0
	s_nop 0
	s_nop 0
	s_nop 0
	s_nop 0
	s_nop 0
	s_nop 0
	s_nop 0
	s_nop 0
	s_nop 0
	s_nop 0
	s_nop 0
	s_nop 0
	s_nop 0
	s_nop 0
	s_nop 0
	s_nop 0
	s_nop 0
	s_nop 0
	s_nop 0
	s_nop 0
	s_nop 0
	s_nop 0
	s_nop 0
	s_nop 0
	s_nop 0
	s_nop 0
	s_nop 0
	s_nop 0
	s_nop 0
	s_nop 0
	s_nop 0
	s_nop 0
	s_nop 0
	s_nop 0
	s_nop 0
	s_nop 0
	s_nop 0
	s_nop 0
	s_nop 0
; __device__ __forceinline__ void attnA_unit(const P2Ctx& C, int b, int h, int qb) {
;     ...
;     if (comp == 0) {
; #pragma unroll
;         for (int cb = 0; cb < 4; ++cb)
; #pragma unroll
;             for (int r = 0; r < 16; ++r) o[cb][r] = o[cb][r] * inv - lam * X2[((qs * 4 + cb) * 16 + r) * 64 + lane];
.LaA_comp0_34:
	v_lshrrev_b32_e32 v242, 5, v219
	v_lshlrev_b32_e32 v242, 4, v242
	v_add_u32_e32 v242, 0x22a00, v242
	ds_read_b128 v[100:103], v242 offset:0
	ds_read_b128 v[104:107], v242 offset:32
	ds_read_b128 v[108:111], v242 offset:64
	ds_read_b128 v[112:115], v242 offset:96
	ds_read_b128 v[116:119], v242 offset:128
	ds_read_b128 v[120:123], v242 offset:160
	ds_read_b128 v[124:127], v242 offset:192
	ds_read_b128 v[128:131], v242 offset:224
	s_waitcnt lgkmcnt(4)
	ds_read_b128 v[132:135], v242 offset:256
	ds_read_b128 v[136:139], v242 offset:288
	ds_read_b128 v[140:143], v242 offset:320
	ds_read_b128 v[144:147], v242 offset:352
	ds_read_b128 v[148:151], v242 offset:384
	ds_read_b128 v[152:155], v242 offset:416
	ds_read_b128 v[156:159], v242 offset:448
	ds_read_b128 v[160:163], v242 offset:480
	s_waitcnt lgkmcnt(6)
	ds_read_b32 v243, v207
	s_nop 7
	s_nop 3
	v_mul_f32_e32 v4, v4, v241
	v_mul_f32_e32 v5, v5, v241
	v_mul_f32_e32 v6, v6, v241
	v_mul_f32_e32 v7, v7, v241
	v_mul_f32_e32 v8, v8, v241
	v_mul_f32_e32 v9, v9, v241
	v_mul_f32_e32 v10, v10, v241
	v_mul_f32_e32 v11, v11, v241
	v_mul_f32_e32 v12, v12, v241
	v_mul_f32_e32 v13, v13, v241
	v_mul_f32_e32 v14, v14, v241
	v_mul_f32_e32 v15, v15, v241
	v_mul_f32_e32 v16, v16, v241
	v_mul_f32_e32 v17, v17, v241
	v_mul_f32_e32 v18, v18, v241
	v_mul_f32_e32 v19, v19, v241
	v_mul_f32_e32 v20, v20, v241
	v_mul_f32_e32 v21, v21, v241
	v_mul_f32_e32 v22, v22, v241
	v_mul_f32_e32 v23, v23, v241
	v_mul_f32_e32 v24, v24, v241
	v_mul_f32_e32 v25, v25, v241
	v_mul_f32_e32 v26, v26, v241
	v_mul_f32_e32 v27, v27, v241
	v_mul_f32_e32 v28, v28, v241
	v_mul_f32_e32 v29, v29, v241
	v_mul_f32_e32 v30, v30, v241
	v_mul_f32_e32 v31, v31, v241
	v_mul_f32_e32 v32, v32, v241
	v_mul_f32_e32 v33, v33, v241
	v_mul_f32_e32 v34, v34, v241
	v_mul_f32_e32 v35, v35, v241
	v_mul_f32_e32 v36, v36, v241
	v_mul_f32_e32 v37, v37, v241
	v_mul_f32_e32 v38, v38, v241
	v_mul_f32_e32 v39, v39, v241
	v_mul_f32_e32 v40, v40, v241
	v_mul_f32_e32 v41, v41, v241
	v_mul_f32_e32 v42, v42, v241
	v_mul_f32_e32 v43, v43, v241
	v_mul_f32_e32 v44, v44, v241
	v_mul_f32_e32 v45, v45, v241
	v_mul_f32_e32 v46, v46, v241
	v_mul_f32_e32 v47, v47, v241
	v_mul_f32_e32 v48, v48, v241
	v_mul_f32_e32 v49, v49, v241
	v_mul_f32_e32 v50, v50, v241
	v_mul_f32_e32 v51, v51, v241
	v_mul_f32_e32 v52, v52, v241
	v_mul_f32_e32 v53, v53, v241
	v_mul_f32_e32 v54, v54, v241
	v_mul_f32_e32 v55, v55, v241
	v_mul_f32_e32 v56, v56, v241
	v_mul_f32_e32 v57, v57, v241
	v_mul_f32_e32 v58, v58, v241
	v_mul_f32_e32 v59, v59, v241
	v_mul_f32_e32 v60, v60, v241
	v_mul_f32_e32 v61, v61, v241
	v_mul_f32_e32 v62, v62, v241
	v_mul_f32_e32 v63, v63, v241
	v_mul_f32_e32 v64, v64, v241
	v_mul_f32_e32 v65, v65, v241
	v_mul_f32_e32 v66, v66, v241
	v_mul_f32_e32 v67, v67, v241
	s_waitcnt lgkmcnt(0)
	s_barrier
	ds_read2st64_b32 v[164:165], v2 offset0:0 offset1:1
	ds_read2st64_b32 v[166:167], v2 offset0:2 offset1:3
	ds_read2st64_b32 v[168:169], v2 offset0:4 offset1:5
	ds_read2st64_b32 v[170:171], v2 offset0:6 offset1:7
	ds_read2st64_b32 v[172:173], v2 offset0:8 offset1:9
	ds_read2st64_b32 v[174:175], v2 offset0:10 offset1:11
	ds_read2st64_b32 v[176:177], v2 offset0:12 offset1:13
	ds_read2st64_b32 v[178:179], v2 offset0:14 offset1:15
	ds_read2st64_b32 v[180:181], v2 offset0:16 offset1:17
	ds_read2st64_b32 v[182:183], v2 offset0:18 offset1:19
	ds_read2st64_b32 v[184:185], v2 offset0:20 offset1:21
	ds_read2st64_b32 v[186:187], v2 offset0:22 offset1:23
	ds_read2st64_b32 v[188:189], v2 offset0:24 offset1:25
	ds_read2st64_b32 v[190:191], v2 offset0:26 offset1:27
	ds_read2st64_b32 v[192:193], v2 offset0:28 offset1:29
	s_waitcnt lgkmcnt(8)
	ds_read2st64_b32 v[194:195], v2 offset0:30 offset1:31
	ds_read2st64_b32 v[68:69], v2 offset0:32 offset1:33
	ds_read2st64_b32 v[70:71], v2 offset0:34 offset1:35
	ds_read2st64_b32 v[72:73], v2 offset0:36 offset1:37
	ds_read2st64_b32 v[74:75], v2 offset0:38 offset1:39
	ds_read2st64_b32 v[76:77], v2 offset0:40 offset1:41
	ds_read2st64_b32 v[78:79], v2 offset0:42 offset1:43
	ds_read2st64_b32 v[80:81], v2 offset0:44 offset1:45
	ds_read2st64_b32 v[82:83], v2 offset0:46 offset1:47
	ds_read2st64_b32 v[84:85], v2 offset0:48 offset1:49
	ds_read2st64_b32 v[86:87], v2 offset0:50 offset1:51
	ds_read2st64_b32 v[88:89], v2 offset0:52 offset1:53
	ds_read2st64_b32 v[90:91], v2 offset0:54 offset1:55
	ds_read2st64_b32 v[92:93], v2 offset0:56 offset1:57
	ds_read2st64_b32 v[94:95], v2 offset0:58 offset1:59
	ds_read2st64_b32 v[96:97], v2 offset0:60 offset1:61
	ds_read2st64_b32 v[98:99], v2 offset0:62 offset1:63
	s_waitcnt lgkmcnt(0)
; __device__ __forceinline__ void subln_store(f32x16 (&o)[4], const float* subg, bf16_t* dst  , int lane) {
;     const int hi = lane >> 5;
;     float ss = 0.f;
; #pragma unroll
;     for (int cb = 0; cb < 4; ++cb)
; #pragma unroll
;         for (int r = 0; r < 16; ++r) ss += o[cb][r] * o[cb][r];
;     ss += __shfl_xor(ss, 32);
;     const float rstd = (1.0f - LAMBDA_INIT) / sqrtf(ss * (1.0f / 128.0f) + EPS);
; __device__ __forceinline__ void attnA_unit(const P2Ctx& C, int b, int h, int qb) {
;     ...
;             for (int r = 0; r < 16; ++r) o[cb][r] = o[cb][r] * inv - lam * X2[((qs * 4 + cb) * 16 + r) * 64 + lane];
;         subln_store(o, C.a->in[I_SUBG], C.AO + qrow * DM + h * 128, lane);
	v_fma_f32 v4, -v243, v164, v4
	v_fma_f32 v5, -v243, v165, v5
	v_fma_f32 v6, -v243, v166, v6
	v_fma_f32 v7, -v243, v167, v7
	v_fma_f32 v8, -v243, v168, v8
	v_fma_f32 v9, -v243, v169, v9
	v_fma_f32 v10, -v243, v170, v10
	v_fma_f32 v11, -v243, v171, v11
	v_fma_f32 v12, -v243, v172, v12
	v_fma_f32 v13, -v243, v173, v13
	v_fma_f32 v14, -v243, v174, v14
	v_fma_f32 v15, -v243, v175, v15
	v_fma_f32 v16, -v243, v176, v16
	v_fma_f32 v17, -v243, v177, v17
	v_fma_f32 v18, -v243, v178, v18
	v_fma_f32 v19, -v243, v179, v19
	v_fma_f32 v20, -v243, v180, v20
	v_fma_f32 v21, -v243, v181, v21
	v_fma_f32 v22, -v243, v182, v22
	v_fma_f32 v23, -v243, v183, v23
	v_fma_f32 v24, -v243, v184, v24
	v_fma_f32 v25, -v243, v185, v25
	v_fma_f32 v26, -v243, v186, v26
	v_fma_f32 v27, -v243, v187, v27
	v_fma_f32 v28, -v243, v188, v28
	v_fma_f32 v29, -v243, v189, v29
	v_fma_f32 v30, -v243, v190, v30
	v_fma_f32 v31, -v243, v191, v31
	v_fma_f32 v32, -v243, v192, v32
	v_fma_f32 v33, -v243, v193, v33
	v_fma_f32 v34, -v243, v194, v34
	v_fma_f32 v35, -v243, v195, v35
	v_fma_f32 v36, -v243, v68, v36
	v_fma_f32 v37, -v243, v69, v37
	v_fma_f32 v38, -v243, v70, v38
	v_fma_f32 v39, -v243, v71, v39
	v_fma_f32 v40, -v243, v72, v40
	v_fma_f32 v41, -v243, v73, v41
	v_fma_f32 v42, -v243, v74, v42
	v_fma_f32 v43, -v243, v75, v43
	v_fma_f32 v44, -v243, v76, v44
	v_fma_f32 v45, -v243, v77, v45
	v_fma_f32 v46, -v243, v78, v46
	v_fma_f32 v47, -v243, v79, v47
	v_fma_f32 v48, -v243, v80, v48
	v_fma_f32 v49, -v243, v81, v49
	v_fma_f32 v50, -v243, v82, v50
	v_fma_f32 v51, -v243, v83, v51
	v_fma_f32 v52, -v243, v84, v52
	v_fma_f32 v53, -v243, v85, v53
	v_fma_f32 v54, -v243, v86, v54
	v_fma_f32 v55, -v243, v87, v55
	v_fma_f32 v56, -v243, v88, v56
	v_fma_f32 v57, -v243, v89, v57
	v_fma_f32 v58, -v243, v90, v58
	v_fma_f32 v59, -v243, v91, v59
	v_fma_f32 v60, -v243, v92, v60
	v_fma_f32 v61, -v243, v93, v61
	v_fma_f32 v62, -v243, v94, v62
	v_fma_f32 v63, -v243, v95, v63
	v_fma_f32 v64, -v243, v96, v64
	v_fma_f32 v65, -v243, v97, v65
	v_fma_f32 v66, -v243, v98, v66
	v_fma_f32 v67, -v243, v99, v67
	v_mul_f32_e32 v245, v4, v4
	v_fmac_f32_e32 v245, v5, v5
	v_fmac_f32_e32 v245, v6, v6
	v_fmac_f32_e32 v245, v7, v7
	v_fmac_f32_e32 v245, v8, v8
	v_fmac_f32_e32 v245, v9, v9
	v_fmac_f32_e32 v245, v10, v10
	v_fmac_f32_e32 v245, v11, v11
	v_fmac_f32_e32 v245, v12, v12
	v_fmac_f32_e32 v245, v13, v13
	v_fmac_f32_e32 v245, v14, v14
	v_fmac_f32_e32 v245, v15, v15
	v_fmac_f32_e32 v245, v16, v16
	v_fmac_f32_e32 v245, v17, v17
	v_fmac_f32_e32 v245, v18, v18
	v_fmac_f32_e32 v245, v19, v19
	v_fmac_f32_e32 v245, v20, v20
	v_fmac_f32_e32 v245, v21, v21
	v_fmac_f32_e32 v245, v22, v22
	v_fmac_f32_e32 v245, v23, v23
	v_fmac_f32_e32 v245, v24, v24
	v_fmac_f32_e32 v245, v25, v25
	v_fmac_f32_e32 v245, v26, v26
	v_fmac_f32_e32 v245, v27, v27
	v_fmac_f32_e32 v245, v28, v28
	v_fmac_f32_e32 v245, v29, v29
	v_fmac_f32_e32 v245, v30, v30
	v_fmac_f32_e32 v245, v31, v31
	v_fmac_f32_e32 v245, v32, v32
	v_fmac_f32_e32 v245, v33, v33
	v_fmac_f32_e32 v245, v34, v34
	v_fmac_f32_e32 v245, v35, v35
	v_fmac_f32_e32 v245, v36, v36
	v_fmac_f32_e32 v245, v37, v37
	v_fmac_f32_e32 v245, v38, v38
	v_fmac_f32_e32 v245, v39, v39
	v_fmac_f32_e32 v245, v40, v40
	v_fmac_f32_e32 v245, v41, v41
	v_fmac_f32_e32 v245, v42, v42
	v_fmac_f32_e32 v245, v43, v43
	v_fmac_f32_e32 v245, v44, v44
	v_fmac_f32_e32 v245, v45, v45
	v_fmac_f32_e32 v245, v46, v46
	v_fmac_f32_e32 v245, v47, v47
	v_fmac_f32_e32 v245, v48, v48
	v_fmac_f32_e32 v245, v49, v49
	v_fmac_f32_e32 v245, v50, v50
	v_fmac_f32_e32 v245, v51, v51
	v_fmac_f32_e32 v245, v52, v52
	v_fmac_f32_e32 v245, v53, v53
	v_fmac_f32_e32 v245, v54, v54
	v_fmac_f32_e32 v245, v55, v55
	v_fmac_f32_e32 v245, v56, v56
	v_fmac_f32_e32 v245, v57, v57
	v_fmac_f32_e32 v245, v58, v58
	v_fmac_f32_e32 v245, v59, v59
	v_fmac_f32_e32 v245, v60, v60
	v_fmac_f32_e32 v245, v61, v61
	v_fmac_f32_e32 v245, v62, v62
	v_fmac_f32_e32 v245, v63, v63
	v_fmac_f32_e32 v245, v64, v64
	v_fmac_f32_e32 v245, v65, v65
	v_fmac_f32_e32 v245, v66, v66
	v_fmac_f32_e32 v245, v67, v67
	v_mov_b32_e32 v246, v245
	s_nop 1
	v_permlane32_swap_b32 v246, v245
	v_add_f32_e32 v245, v246, v245
	v_mov_b32_e32 v246, 0x3c000000
	v_fmaak_f32 v245, v245, v246, 0x358637bd
	v_rsq_f32_e32 v245, v245
	s_nop 0
	v_mul_f32_e32 v245, 0x3f4ccccd, v245
	s_lshl_b32 s6, s11, 11
	s_add_i32 s6, s6, s15
	s_lshl_b32 s6, s6, 11
	s_lshl_b32 s7, s81, 1
	s_add_i32 s6, s6, s7
	s_add_u32 s20, s70, s6
	s_addc_u32 s21, s71, 0
	v_and_b32_e32 v242, 31, v219
	v_lshlrev_b32_e32 v242, 11, v242
	v_lshrrev_b32_e32 v243, 5, v219
	v_lshl_add_u32 v242, v243, 3, v242
	s_waitcnt vmcnt(0)
; __device__ __forceinline__ unsigned pk_bf16(float lo, float hi) { f32x2 v = {lo, hi}; bf16x2_t b = __builtin_convertvector(v, bf16x2_t); return __builtin_bit_cast(unsigned, b); }
; __device__ __forceinline__ void subln_store(f32x16 (&o)[4], const float* subg, bf16_t* dst  , int lane) {
;     ...
;     f32x4 sg[4][4];
; #pragma unroll
;     for (int cb = 0; cb < 4; ++cb)
; #pragma unroll
;         for (int g = 0; g < 4; ++g) sg[cb][g] = *(const f32x4*)(subg + 32 * cb + 8 * g + 4 * hi);
;     asm volatile("" ::: "memory");
; #pragma unroll
;     for (int cb = 0; cb < 4; ++cb)
; #pragma unroll
;         for (int g = 0; g < 4; ++g) { const int dv0 = 32 * cb + 8 * g + 4 * hi; const f32x4 s4 = sg[cb][g];
;             u32x2 w; w.x = pk_bf16(o[cb][4 * g + 0] * rstd * s4[0], o[cb][4 * g + 1] * rstd * s4[1]); w.y = pk_bf16(o[cb][4 * g + 2] * rstd * s4[2], o[cb][4 * g + 3] * rstd * s4[3]);
;             *(u32x2*)(dst + dv0) = w; }
	v_mul_f32_e32 v4, v4, v245
	v_mul_f32_e32 v5, v5, v245
	v_mul_f32_e32 v6, v6, v245
	v_mul_f32_e32 v7, v7, v245
	v_mul_f32_e32 v4, v4, v100
	v_mul_f32_e32 v5, v5, v101
	v_mul_f32_e32 v6, v6, v102
	v_mul_f32_e32 v7, v7, v103
	v_cvt_pk_bf16_f32 v68, v4, v5
	v_cvt_pk_bf16_f32 v69, v6, v7
	global_store_dwordx2 v242, v[68:69], s[20:21] offset:0
	v_mul_f32_e32 v8, v8, v245
	v_mul_f32_e32 v9, v9, v245
	v_mul_f32_e32 v10, v10, v245
	v_mul_f32_e32 v11, v11, v245
	v_mul_f32_e32 v8, v8, v104
	v_mul_f32_e32 v9, v9, v105
	v_mul_f32_e32 v10, v10, v106
	v_mul_f32_e32 v11, v11, v107
	v_cvt_pk_bf16_f32 v70, v8, v9
	v_cvt_pk_bf16_f32 v71, v10, v11
	global_store_dwordx2 v242, v[70:71], s[20:21] offset:16
	v_mul_f32_e32 v12, v12, v245
	v_mul_f32_e32 v13, v13, v245
	v_mul_f32_e32 v14, v14, v245
	v_mul_f32_e32 v15, v15, v245
	v_mul_f32_e32 v12, v12, v108
	v_mul_f32_e32 v13, v13, v109
	v_mul_f32_e32 v14, v14, v110
	v_mul_f32_e32 v15, v15, v111
	v_cvt_pk_bf16_f32 v68, v12, v13
	v_cvt_pk_bf16_f32 v69, v14, v15
	global_store_dwordx2 v242, v[68:69], s[20:21] offset:32
	v_mul_f32_e32 v16, v16, v245
	v_mul_f32_e32 v17, v17, v245
	v_mul_f32_e32 v18, v18, v245
	v_mul_f32_e32 v19, v19, v245
	v_mul_f32_e32 v16, v16, v112
	v_mul_f32_e32 v17, v17, v113
	v_mul_f32_e32 v18, v18, v114
	v_mul_f32_e32 v19, v19, v115
	v_cvt_pk_bf16_f32 v70, v16, v17
	v_cvt_pk_bf16_f32 v71, v18, v19
	global_store_dwordx2 v242, v[70:71], s[20:21] offset:48
	v_mul_f32_e32 v20, v20, v245
	v_mul_f32_e32 v21, v21, v245
	v_mul_f32_e32 v22, v22, v245
	v_mul_f32_e32 v23, v23, v245
	v_mul_f32_e32 v20, v20, v116
	v_mul_f32_e32 v21, v21, v117
	v_mul_f32_e32 v22, v22, v118
	v_mul_f32_e32 v23, v23, v119
	v_cvt_pk_bf16_f32 v68, v20, v21
	v_cvt_pk_bf16_f32 v69, v22, v23
	global_store_dwordx2 v242, v[68:69], s[20:21] offset:64
	v_mul_f32_e32 v24, v24, v245
	v_mul_f32_e32 v25, v25, v245
	v_mul_f32_e32 v26, v26, v245
	v_mul_f32_e32 v27, v27, v245
	v_mul_f32_e32 v24, v24, v120
	v_mul_f32_e32 v25, v25, v121
	v_mul_f32_e32 v26, v26, v122
	v_mul_f32_e32 v27, v27, v123
	v_cvt_pk_bf16_f32 v70, v24, v25
	v_cvt_pk_bf16_f32 v71, v26, v27
	global_store_dwordx2 v242, v[70:71], s[20:21] offset:80
	v_mul_f32_e32 v28, v28, v245
	v_mul_f32_e32 v29, v29, v245
	v_mul_f32_e32 v30, v30, v245
	v_mul_f32_e32 v31, v31, v245
	v_mul_f32_e32 v28, v28, v124
	v_mul_f32_e32 v29, v29, v125
	v_mul_f32_e32 v30, v30, v126
	v_mul_f32_e32 v31, v31, v127
	v_cvt_pk_bf16_f32 v68, v28, v29
	v_cvt_pk_bf16_f32 v69, v30, v31
	global_store_dwordx2 v242, v[68:69], s[20:21] offset:96
	v_mul_f32_e32 v32, v32, v245
	v_mul_f32_e32 v33, v33, v245
	v_mul_f32_e32 v34, v34, v245
	v_mul_f32_e32 v35, v35, v245
	v_mul_f32_e32 v32, v32, v128
	v_mul_f32_e32 v33, v33, v129
	v_mul_f32_e32 v34, v34, v130
	v_mul_f32_e32 v35, v35, v131
	v_cvt_pk_bf16_f32 v70, v32, v33
	v_cvt_pk_bf16_f32 v71, v34, v35
	global_store_dwordx2 v242, v[70:71], s[20:21] offset:112
	v_mul_f32_e32 v36, v36, v245
	v_mul_f32_e32 v37, v37, v245
	v_mul_f32_e32 v38, v38, v245
	v_mul_f32_e32 v39, v39, v245
	v_mul_f32_e32 v36, v36, v132
	v_mul_f32_e32 v37, v37, v133
	v_mul_f32_e32 v38, v38, v134
	v_mul_f32_e32 v39, v39, v135
	v_cvt_pk_bf16_f32 v68, v36, v37
	v_cvt_pk_bf16_f32 v69, v38, v39
	global_store_dwordx2 v242, v[68:69], s[20:21] offset:128
	v_mul_f32_e32 v40, v40, v245
	v_mul_f32_e32 v41, v41, v245
	v_mul_f32_e32 v42, v42, v245
	v_mul_f32_e32 v43, v43, v245
	v_mul_f32_e32 v40, v40, v136
	v_mul_f32_e32 v41, v41, v137
	v_mul_f32_e32 v42, v42, v138
	v_mul_f32_e32 v43, v43, v139
	v_cvt_pk_bf16_f32 v70, v40, v41
	v_cvt_pk_bf16_f32 v71, v42, v43
	global_store_dwordx2 v242, v[70:71], s[20:21] offset:144
	v_mul_f32_e32 v44, v44, v245
	v_mul_f32_e32 v45, v45, v245
	v_mul_f32_e32 v46, v46, v245
	v_mul_f32_e32 v47, v47, v245
	v_mul_f32_e32 v44, v44, v140
	v_mul_f32_e32 v45, v45, v141
	v_mul_f32_e32 v46, v46, v142
	v_mul_f32_e32 v47, v47, v143
	v_cvt_pk_bf16_f32 v68, v44, v45
	v_cvt_pk_bf16_f32 v69, v46, v47
	global_store_dwordx2 v242, v[68:69], s[20:21] offset:160
	v_mul_f32_e32 v48, v48, v245
	v_mul_f32_e32 v49, v49, v245
	v_mul_f32_e32 v50, v50, v245
	v_mul_f32_e32 v51, v51, v245
	v_mul_f32_e32 v48, v48, v144
	v_mul_f32_e32 v49, v49, v145
	v_mul_f32_e32 v50, v50, v146
	v_mul_f32_e32 v51, v51, v147
	v_cvt_pk_bf16_f32 v70, v48, v49
	v_cvt_pk_bf16_f32 v71, v50, v51
	global_store_dwordx2 v242, v[70:71], s[20:21] offset:176
	v_mul_f32_e32 v52, v52, v245
	v_mul_f32_e32 v53, v53, v245
	v_mul_f32_e32 v54, v54, v245
	v_mul_f32_e32 v55, v55, v245
	v_mul_f32_e32 v52, v52, v148
	v_mul_f32_e32 v53, v53, v149
	v_mul_f32_e32 v54, v54, v150
	v_mul_f32_e32 v55, v55, v151
	v_cvt_pk_bf16_f32 v68, v52, v53
	v_cvt_pk_bf16_f32 v69, v54, v55
	global_store_dwordx2 v242, v[68:69], s[20:21] offset:192
	v_mul_f32_e32 v56, v56, v245
	v_mul_f32_e32 v57, v57, v245
	v_mul_f32_e32 v58, v58, v245
	v_mul_f32_e32 v59, v59, v245
	v_mul_f32_e32 v56, v56, v152
	v_mul_f32_e32 v57, v57, v153
	v_mul_f32_e32 v58, v58, v154
	v_mul_f32_e32 v59, v59, v155
	v_cvt_pk_bf16_f32 v70, v56, v57
	v_cvt_pk_bf16_f32 v71, v58, v59
	global_store_dwordx2 v242, v[70:71], s[20:21] offset:208
	v_mul_f32_e32 v60, v60, v245
	v_mul_f32_e32 v61, v61, v245
	v_mul_f32_e32 v62, v62, v245
	v_mul_f32_e32 v63, v63, v245
	v_mul_f32_e32 v60, v60, v156
	v_mul_f32_e32 v61, v61, v157
	v_mul_f32_e32 v62, v62, v158
	v_mul_f32_e32 v63, v63, v159
	v_cvt_pk_bf16_f32 v68, v60, v61
	v_cvt_pk_bf16_f32 v69, v62, v63
	global_store_dwordx2 v242, v[68:69], s[20:21] offset:224
	v_mul_f32_e32 v64, v64, v245
	v_mul_f32_e32 v65, v65, v245
	v_mul_f32_e32 v66, v66, v245
	v_mul_f32_e32 v67, v67, v245
	v_mul_f32_e32 v64, v64, v160
	v_mul_f32_e32 v65, v65, v161
	v_mul_f32_e32 v66, v66, v162
	v_mul_f32_e32 v67, v67, v163
	v_cvt_pk_bf16_f32 v70, v64, v65
	v_cvt_pk_bf16_f32 v71, v66, v67
	global_store_dwordx2 v242, v[70:71], s[20:21] offset:240
